# pool_prep: the 16 row loads of each 8-row pass issued together at the top of the pass instead of load/vmcnt(0)/use per row
# baseline (speedup 1.0000x reference)
; DI unsigned pk2(float lo, float hi) { const f32x2v v = {lo, hi}; const bf16x2v b = __builtin_convertvector(v, bf16x2v); return __builtin_bit_cast(unsigned, b); }
; DI void pool_prep(const Params& P, LAS unsigned char* lds) {
;     ...
;         if (it < 1024) { const int b = it >> 7, t0 = (it & 127) * 16; const size_t rb = (size_t)b * 2048;
;             f32x4 sum = {0.f, 0.f, 0.f, 0.f};
;             for (int j = 1; j < w; ++j) { const int tt = t0 - j; if (tt >= 0) { const float rs = rsl[15 - j]; sum += *(const f32x4*)(X + (rb + tt) * DM + c4) * g4 * rs; } }
; #pragma unroll 8
;             for (int t = t0; t < t0 + 16; ++t) { const float rs = rsl[t - t0 + 15]; const f32x4 cur = *(const f32x4*)(X + (rb + t) * DM + c4) * g4 * rs;
;                 sum += cur; const float ic = __builtin_amdgcn_rcpf((float)(t + 1 < w ? t + 1 : w)); const f32x4 d = sum * ic - cur;
;                 u32x2 o; o.x = pk2(d[0], d[1]); o.y = pk2(d[2], d[3]); *(u32x2*)(DF + (rb + t) * DM + c4) = o;
;                 if (t >= 2033) *(f32x4*)(P.out + OUT_POOLP + ((size_t)b * 15 + (t - 2033)) * DM + c4) = cur;
;                 const int tt = t - w + 1; if (tt >= 0) { const float r2 = rsl[tt - t0 + 15]; sum -= *(const f32x4*)(X + (rb + tt) * DM + c4) * g4 * r2; } }
.LBB0_124:
	v_lshl_add_u64 v[18:19], s[26:27], 0, v[14:15]
	s_mov_b64 s[16:17], 0x1000
	v_add_co_u32_e32 v136, vcc, 0xabc0000, v18
	s_nop 1
	v_addc_co_u32_e32 v137, vcc, 0, v19, vcc
	global_load_dwordx4 v[72:75], v[136:137], off
	v_lshl_add_u64 v[136:137], v[136:137], 0, s[16:17]
	global_load_dwordx4 v[76:79], v[136:137], off
	v_lshl_add_u64 v[136:137], v[136:137], 0, s[16:17]
	global_load_dwordx4 v[80:83], v[136:137], off
	v_lshl_add_u64 v[136:137], v[136:137], 0, s[16:17]
	global_load_dwordx4 v[84:87], v[136:137], off
	v_lshl_add_u64 v[136:137], v[136:137], 0, s[16:17]
	global_load_dwordx4 v[88:91], v[136:137], off
	v_lshl_add_u64 v[136:137], v[136:137], 0, s[16:17]
	global_load_dwordx4 v[92:95], v[136:137], off
	v_lshl_add_u64 v[136:137], v[136:137], 0, s[16:17]
	global_load_dwordx4 v[96:99], v[136:137], off
	v_lshl_add_u64 v[136:137], v[136:137], 0, s[16:17]
	global_load_dwordx4 v[100:103], v[136:137], off
	v_add_u32_e32 v140, s3, v51
	v_mov_b32_e32 v139, 0
	v_add_u32_e32 v138, 1, v140
	v_max_i32_e32 v138, 0, v138
	v_lshl_add_u64 v[136:137], v[8:9], 0, v[138:139]
	v_lshlrev_b64 v[136:137], 12, v[136:137]
	v_lshl_add_u64 v[136:137], v[30:31], 0, v[136:137]
	global_load_dwordx4 v[104:107], v[136:137], off
	v_add_u32_e32 v138, 2, v140
	v_max_i32_e32 v138, 0, v138
	v_lshl_add_u64 v[136:137], v[8:9], 0, v[138:139]
	v_lshlrev_b64 v[136:137], 12, v[136:137]
	v_lshl_add_u64 v[136:137], v[30:31], 0, v[136:137]
	global_load_dwordx4 v[108:111], v[136:137], off
	v_add_u32_e32 v138, 3, v140
	v_max_i32_e32 v138, 0, v138
	v_lshl_add_u64 v[136:137], v[8:9], 0, v[138:139]
	v_lshlrev_b64 v[136:137], 12, v[136:137]
	v_lshl_add_u64 v[136:137], v[30:31], 0, v[136:137]
	global_load_dwordx4 v[112:115], v[136:137], off
	v_add_u32_e32 v138, 4, v140
	v_max_i32_e32 v138, 0, v138
	v_lshl_add_u64 v[136:137], v[8:9], 0, v[138:139]
	v_lshlrev_b64 v[136:137], 12, v[136:137]
	v_lshl_add_u64 v[136:137], v[30:31], 0, v[136:137]
	global_load_dwordx4 v[116:119], v[136:137], off
	v_add_u32_e32 v138, 5, v140
	v_max_i32_e32 v138, 0, v138
	v_lshl_add_u64 v[136:137], v[8:9], 0, v[138:139]
	v_lshlrev_b64 v[136:137], 12, v[136:137]
	v_lshl_add_u64 v[136:137], v[30:31], 0, v[136:137]
	global_load_dwordx4 v[120:123], v[136:137], off
	v_add_u32_e32 v138, 6, v140
	v_max_i32_e32 v138, 0, v138
	v_lshl_add_u64 v[136:137], v[8:9], 0, v[138:139]
	v_lshlrev_b64 v[136:137], 12, v[136:137]
	v_lshl_add_u64 v[136:137], v[30:31], 0, v[136:137]
	global_load_dwordx4 v[124:127], v[136:137], off
	v_add_u32_e32 v138, 7, v140
	v_max_i32_e32 v138, 0, v138
	v_lshl_add_u64 v[136:137], v[8:9], 0, v[138:139]
	v_lshlrev_b64 v[136:137], 12, v[136:137]
	v_lshl_add_u64 v[136:137], v[30:31], 0, v[136:137]
	global_load_dwordx4 v[128:131], v[136:137], off
	v_add_u32_e32 v138, 8, v140
	v_max_i32_e32 v138, 0, v138
	v_lshl_add_u64 v[136:137], v[8:9], 0, v[138:139]
	v_lshlrev_b64 v[136:137], 12, v[136:137]
	v_lshl_add_u64 v[136:137], v[30:31], 0, v[136:137]
	global_load_dwordx4 v[132:135], v[136:137], off
	s_waitcnt vmcnt(0)
	v_add_co_u32_e32 v4, vcc, 0xabc0000, v18
	ds_read_b32 v24, v59
	s_nop 0
	v_addc_co_u32_e32 v5, vcc, 0, v19, vcc
	v_mov_b32_e32 v4, v72
	v_mov_b32_e32 v5, v73
	v_mov_b32_e32 v6, v74
	v_mov_b32_e32 v7, v75
	v_add_u32_e32 v60, s3, v50
	v_add_u32_e32 v23, 1, v60
	v_min_u32_e32 v23, v23, v39
	v_cvt_f32_ubyte0_e32 v23, v23
	v_pk_mul_f32 v[42:43], v[2:3], v[6:7]
	v_pk_mul_f32 v[48:49], v[0:1], v[4:5]
	s_waitcnt lgkmcnt(0)
	v_pk_mul_f32 v[6:7], v[42:43], v[24:25] op_sel_hi:[1,0]
	v_pk_mul_f32 v[4:5], v[48:49], v[24:25] op_sel_hi:[1,0]
	v_pk_fma_f32 v[46:47], v[42:43], v[24:25], v[46:47] op_sel_hi:[1,0,1]
	v_pk_fma_f32 v[44:45], v[48:49], v[24:25], v[44:45] op_sel_hi:[1,0,1]
	v_rcp_iflag_f32_e32 v24, v23
	s_nop 0
	v_pk_fma_f32 v[42:43], v[46:47], v[24:25], v[6:7] op_sel_hi:[1,0,1] neg_lo:[0,0,1] neg_hi:[0,0,1]
	v_pk_fma_f32 v[48:49], v[44:45], v[24:25], v[4:5] op_sel_hi:[1,0,1] neg_lo:[0,0,1] neg_hi:[0,0,1]
	s_nop 0
	v_cvt_pk_bf16_f32 v48, v48, v49
	v_cvt_pk_bf16_f32 v49, v42, v43
	v_lshl_add_u64 v[42:43], s[26:27], 0, v[12:13]
	v_add_co_u32_e32 v62, vcc, 0x16560000, v42
	s_nop 1
	v_addc_co_u32_e32 v63, vcc, 0, v43, vcc
	v_cmp_lt_u32_e32 vcc, s93, v60
	global_store_dwordx2 v[62:63], v[48:49], off
	s_and_saveexec_b64 s[16:17], vcc
	s_cbranch_execz .LBB0_126
	s_load_dwordx2 s[18:19], s[0:1], 0x150
	v_add_u32_e32 v24, 0xfffff80f, v60
	v_lshl_add_u64 v[48:49], v[10:11], 0, v[24:25]
	v_lshlrev_b64 v[48:49], 12, v[48:49]
	v_mov_b32_e32 v23, v25
	s_waitcnt lgkmcnt(0)
	v_lshl_add_u64 v[48:49], s[18:19], 0, v[48:49]
	v_lshl_add_u64 v[48:49], v[48:49], 0, v[22:23]
	v_add_co_u32_e32 v48, vcc, 0x4400000, v48
	s_nop 1
	v_addc_co_u32_e32 v49, vcc, 0, v49, vcc
	global_store_dwordx4 v[48:49], v[4:7], off
.LBB0_126:
	s_or_b64 exec, exec, s[16:17]
	v_add_u32_e32 v61, s3, v51
	v_cmp_lt_i32_e32 vcc, -2, v61
	v_add_u32_e32 v24, 1, v61
	v_add_u32_e32 v23, v59, v58
	s_and_saveexec_b64 s[16:17], vcc
	s_cbranch_execz .LBB0_128
	v_lshl_add_u64 v[4:5], v[8:9], 0, v[24:25]
	v_lshlrev_b64 v[4:5], 12, v[4:5]
	v_lshl_add_u64 v[4:5], v[30:31], 0, v[4:5]
	v_mov_b32_e32 v4, v104
	v_mov_b32_e32 v5, v105
	v_mov_b32_e32 v6, v106
	v_mov_b32_e32 v7, v107
	ds_read_b32 v48, v23 offset:4
	v_pk_mul_f32 v[6:7], v[2:3], v[6:7]
	v_pk_mul_f32 v[4:5], v[0:1], v[4:5]
	s_waitcnt lgkmcnt(0)
	v_pk_fma_f32 v[46:47], v[6:7], v[48:49], v[46:47] op_sel_hi:[1,0,1] neg_lo:[1,0,0] neg_hi:[1,0,0]
	v_pk_fma_f32 v[44:45], v[4:5], v[48:49], v[44:45] op_sel_hi:[1,0,1] neg_lo:[1,0,0] neg_hi:[1,0,0]
; DI unsigned pk2(float lo, float hi) { const f32x2v v = {lo, hi}; const bf16x2v b = __builtin_convertvector(v, bf16x2v); return __builtin_bit_cast(unsigned, b); }
; DI void pool_prep(const Params& P, LAS unsigned char* lds) {
;     ...
;         if (it < 1024) { const int b = it >> 7, t0 = (it & 127) * 16; const size_t rb = (size_t)b * 2048;
;             f32x4 sum = {0.f, 0.f, 0.f, 0.f};
;             for (int j = 1; j < w; ++j) { const int tt = t0 - j; if (tt >= 0) { const float rs = rsl[15 - j]; sum += *(const f32x4*)(X + (rb + tt) * DM + c4) * g4 * rs; } }
; #pragma unroll 8
;             for (int t = t0; t < t0 + 16; ++t) { const float rs = rsl[t - t0 + 15]; const f32x4 cur = *(const f32x4*)(X + (rb + t) * DM + c4) * g4 * rs;
;                 sum += cur; const float ic = __builtin_amdgcn_rcpf((float)(t + 1 < w ? t + 1 : w)); const f32x4 d = sum * ic - cur;
;                 u32x2 o; o.x = pk2(d[0], d[1]); o.y = pk2(d[2], d[3]); *(u32x2*)(DF + (rb + t) * DM + c4) = o;
;                 if (t >= 2033) *(f32x4*)(P.out + OUT_POOLP + ((size_t)b * 15 + (t - 2033)) * DM + c4) = cur;
;                 const int tt = t - w + 1; if (tt >= 0) { const float r2 = rsl[tt - t0 + 15]; sum -= *(const f32x4*)(X + (rb + tt) * DM + c4) * g4 * r2; } }
.LBB0_128:
	s_or_b64 exec, exec, s[16:17]
	v_add_co_u32_e32 v4, vcc, 0xabc1000, v18
	ds_read_b32 v48, v59 offset:4
	s_nop 0
	v_addc_co_u32_e32 v5, vcc, 0, v19, vcc
	v_mov_b32_e32 v4, v76
	v_mov_b32_e32 v5, v77
	v_mov_b32_e32 v6, v78
	v_mov_b32_e32 v7, v79
	s_movk_i32 s16, 0x7ef
	v_cmp_lt_u32_e64 s[38:39], s16, v60
	v_pk_mul_f32 v[62:63], v[2:3], v[6:7]
	v_pk_mul_f32 v[64:65], v[0:1], v[4:5]
	s_waitcnt lgkmcnt(0)
	v_pk_mul_f32 v[6:7], v[62:63], v[48:49] op_sel_hi:[1,0]
	v_pk_mul_f32 v[4:5], v[64:65], v[48:49] op_sel_hi:[1,0]
	v_pk_fma_f32 v[46:47], v[62:63], v[48:49], v[46:47] op_sel_hi:[1,0,1]
	v_pk_fma_f32 v[44:45], v[64:65], v[48:49], v[44:45] op_sel_hi:[1,0,1]
	v_add_u32_e32 v48, 2, v60
	v_min_u32_e32 v48, v48, v39
	v_cvt_f32_ubyte0_e32 v48, v48
	v_rcp_iflag_f32_e32 v48, v48
	s_nop 0
	v_pk_fma_f32 v[62:63], v[46:47], v[48:49], v[6:7] op_sel_hi:[1,0,1] neg_lo:[0,0,1] neg_hi:[0,0,1]
	v_pk_fma_f32 v[48:49], v[44:45], v[48:49], v[4:5] op_sel_hi:[1,0,1] neg_lo:[0,0,1] neg_hi:[0,0,1]
	s_nop 0
	v_cvt_pk_bf16_f32 v48, v48, v49
	v_cvt_pk_bf16_f32 v49, v62, v63
	v_add_co_u32_e32 v62, vcc, 0x16560000, v42
	s_nop 1
	v_addc_co_u32_e32 v63, vcc, 0, v43, vcc
	global_store_dwordx2 v[62:63], v[48:49], off offset:2048
	s_and_saveexec_b64 s[16:17], s[38:39]
	s_cbranch_execz .LBB0_130
	s_load_dwordx2 s[18:19], s[0:1], 0x150
	s_waitcnt lgkmcnt(0)
	v_lshl_add_u64 v[48:49], s[18:19], 0, v[16:17]
	v_add_co_u32_e32 v48, vcc, 0xffffa000, v48
	s_nop 1
	v_addc_co_u32_e32 v49, vcc, -1, v49, vcc
	global_store_dwordx4 v[48:49], v[4:7], off
.LBB0_130:
	s_or_b64 exec, exec, s[16:17]
	v_cmp_lt_i32_e32 vcc, -2, v24
	v_add_u32_e32 v24, 2, v61
	s_and_saveexec_b64 s[16:17], vcc
	s_cbranch_execz .LBB0_132
	v_lshl_add_u64 v[4:5], v[8:9], 0, v[24:25]
	v_lshlrev_b64 v[4:5], 12, v[4:5]
	v_lshl_add_u64 v[4:5], v[30:31], 0, v[4:5]
	v_mov_b32_e32 v4, v108
	v_mov_b32_e32 v5, v109
	v_mov_b32_e32 v6, v110
	v_mov_b32_e32 v7, v111
	ds_read_b32 v48, v23 offset:8
	v_pk_mul_f32 v[6:7], v[2:3], v[6:7]
	v_pk_mul_f32 v[4:5], v[0:1], v[4:5]
	s_waitcnt lgkmcnt(0)
	v_pk_fma_f32 v[46:47], v[6:7], v[48:49], v[46:47] op_sel_hi:[1,0,1] neg_lo:[1,0,0] neg_hi:[1,0,0]
	v_pk_fma_f32 v[44:45], v[4:5], v[48:49], v[44:45] op_sel_hi:[1,0,1] neg_lo:[1,0,0] neg_hi:[1,0,0]
.LBB0_132:
	s_or_b64 exec, exec, s[16:17]
	v_add_co_u32_e32 v4, vcc, 0xabc2000, v18
	ds_read_b32 v48, v59 offset:8
	s_nop 0
	v_addc_co_u32_e32 v5, vcc, 0, v19, vcc
	v_mov_b32_e32 v4, v80
	v_mov_b32_e32 v5, v81
	v_mov_b32_e32 v6, v82
	v_mov_b32_e32 v7, v83
	v_pk_mul_f32 v[62:63], v[2:3], v[6:7]
	v_pk_mul_f32 v[64:65], v[0:1], v[4:5]
	s_waitcnt lgkmcnt(0)
	v_pk_mul_f32 v[6:7], v[62:63], v[48:49] op_sel_hi:[1,0]
	v_pk_fma_f32 v[46:47], v[62:63], v[48:49], v[46:47] op_sel_hi:[1,0,1]
	v_add_u32_e32 v62, 3, v60
	v_pk_mul_f32 v[4:5], v[64:65], v[48:49] op_sel_hi:[1,0]
	v_pk_fma_f32 v[48:49], v[64:65], v[48:49], v[44:45] op_sel_hi:[1,0,1]
	v_min_u32_e32 v44, v62, v39
	v_cvt_f32_ubyte0_e32 v44, v44
	v_rcp_iflag_f32_e32 v44, v44
	s_nop 0
	v_pk_fma_f32 v[64:65], v[46:47], v[44:45], v[6:7] op_sel_hi:[1,0,1] neg_lo:[0,0,1] neg_hi:[0,0,1]
	v_pk_fma_f32 v[44:45], v[48:49], v[44:45], v[4:5] op_sel_hi:[1,0,1] neg_lo:[0,0,1] neg_hi:[0,0,1]
	s_nop 0
	v_cvt_pk_bf16_f32 v44, v44, v45
	v_cvt_pk_bf16_f32 v45, v64, v65
	v_add_co_u32_e32 v64, vcc, 0x16561000, v42
	s_nop 1
	v_addc_co_u32_e32 v65, vcc, 0, v43, vcc
	global_store_dwordx2 v[64:65], v[44:45], off
	s_and_saveexec_b64 s[16:17], s[38:39]
	s_cbranch_execz .LBB0_134
	s_load_dwordx2 s[18:19], s[0:1], 0x150
	s_waitcnt lgkmcnt(0)
	v_lshl_add_u64 v[44:45], s[18:19], 0, v[16:17]
	v_add_co_u32_e32 v44, vcc, 0xffffb000, v44
	s_nop 1
	v_addc_co_u32_e32 v45, vcc, -1, v45, vcc
	global_store_dwordx4 v[44:45], v[4:7], off
.LBB0_134:
	s_or_b64 exec, exec, s[16:17]
	v_cmp_lt_i32_e32 vcc, -2, v24
	v_add_u32_e32 v24, 3, v61
	s_and_saveexec_b64 s[16:17], vcc
	s_cbranch_execz .LBB0_136
	v_lshl_add_u64 v[4:5], v[8:9], 0, v[24:25]
	v_lshlrev_b64 v[4:5], 12, v[4:5]
	v_lshl_add_u64 v[4:5], v[30:31], 0, v[4:5]
	v_mov_b32_e32 v4, v112
	v_mov_b32_e32 v5, v113
	v_mov_b32_e32 v6, v114
	v_mov_b32_e32 v7, v115
	ds_read_b32 v44, v23 offset:12
	v_pk_mul_f32 v[6:7], v[2:3], v[6:7]
	v_pk_mul_f32 v[4:5], v[0:1], v[4:5]
	s_waitcnt lgkmcnt(0)
	v_pk_fma_f32 v[46:47], v[6:7], v[44:45], v[46:47] op_sel_hi:[1,0,1] neg_lo:[1,0,0] neg_hi:[1,0,0]
	v_pk_fma_f32 v[48:49], v[4:5], v[44:45], v[48:49] op_sel_hi:[1,0,1] neg_lo:[1,0,0] neg_hi:[1,0,0]
.LBB0_136:
	s_or_b64 exec, exec, s[16:17]
	v_add_co_u32_e32 v4, vcc, 0xabc3000, v18
	ds_read_b32 v64, v59 offset:12
	s_nop 0
	v_addc_co_u32_e32 v5, vcc, 0, v19, vcc
	v_mov_b32_e32 v4, v84
	v_mov_b32_e32 v5, v85
	v_mov_b32_e32 v6, v86
	v_mov_b32_e32 v7, v87
	v_pk_mul_f32 v[44:45], v[2:3], v[6:7]
	v_pk_mul_f32 v[66:67], v[0:1], v[4:5]
	s_waitcnt lgkmcnt(0)
	v_pk_mul_f32 v[6:7], v[44:45], v[64:65] op_sel_hi:[1,0]
	v_pk_fma_f32 v[44:45], v[44:45], v[64:65], v[46:47] op_sel_hi:[1,0,1]
	v_pk_fma_f32 v[46:47], v[66:67], v[64:65], v[48:49] op_sel_hi:[1,0,1]
	v_add_u32_e32 v48, 4, v60
	v_min_u32_e32 v48, v48, v39
	v_cvt_f32_ubyte0_e32 v48, v48
	v_rcp_iflag_f32_e32 v48, v48
	v_pk_mul_f32 v[4:5], v[66:67], v[64:65] op_sel_hi:[1,0]
	v_pk_fma_f32 v[64:65], v[44:45], v[48:49], v[6:7] op_sel_hi:[1,0,1] neg_lo:[0,0,1] neg_hi:[0,0,1]
	v_pk_fma_f32 v[48:49], v[46:47], v[48:49], v[4:5] op_sel_hi:[1,0,1] neg_lo:[0,0,1] neg_hi:[0,0,1]
	s_nop 0
	v_cvt_pk_bf16_f32 v48, v48, v49
	v_cvt_pk_bf16_f32 v49, v64, v65
	v_add_co_u32_e32 v64, vcc, 0x16561000, v42
	s_nop 1
	v_addc_co_u32_e32 v65, vcc, 0, v43, vcc
	v_cmp_lt_u32_e32 vcc, s93, v62
	global_store_dwordx2 v[64:65], v[48:49], off offset:2048
	s_and_saveexec_b64 s[16:17], vcc
	s_cbranch_execz .LBB0_138
	s_load_dwordx2 s[18:19], s[0:1], 0x150
	s_waitcnt lgkmcnt(0)
	v_lshl_add_u64 v[48:49], s[18:19], 0, v[16:17]
	v_add_co_u32_e32 v48, vcc, 0xffffc000, v48
	s_nop 1
	v_addc_co_u32_e32 v49, vcc, -1, v49, vcc
	global_store_dwordx4 v[48:49], v[4:7], off
; DI unsigned pk2(float lo, float hi) { const f32x2v v = {lo, hi}; const bf16x2v b = __builtin_convertvector(v, bf16x2v); return __builtin_bit_cast(unsigned, b); }
; DI void pool_prep(const Params& P, LAS unsigned char* lds) {
;     ...
;         if (it < 1024) { const int b = it >> 7, t0 = (it & 127) * 16; const size_t rb = (size_t)b * 2048;
;             f32x4 sum = {0.f, 0.f, 0.f, 0.f};
;             for (int j = 1; j < w; ++j) { const int tt = t0 - j; if (tt >= 0) { const float rs = rsl[15 - j]; sum += *(const f32x4*)(X + (rb + tt) * DM + c4) * g4 * rs; } }
; #pragma unroll 8
;             for (int t = t0; t < t0 + 16; ++t) { const float rs = rsl[t - t0 + 15]; const f32x4 cur = *(const f32x4*)(X + (rb + t) * DM + c4) * g4 * rs;
;                 sum += cur; const float ic = __builtin_amdgcn_rcpf((float)(t + 1 < w ? t + 1 : w)); const f32x4 d = sum * ic - cur;
;                 u32x2 o; o.x = pk2(d[0], d[1]); o.y = pk2(d[2], d[3]); *(u32x2*)(DF + (rb + t) * DM + c4) = o;
;                 if (t >= 2033) *(f32x4*)(P.out + OUT_POOLP + ((size_t)b * 15 + (t - 2033)) * DM + c4) = cur;
;                 const int tt = t - w + 1; if (tt >= 0) { const float r2 = rsl[tt - t0 + 15]; sum -= *(const f32x4*)(X + (rb + tt) * DM + c4) * g4 * r2; } }
.LBB0_138:
	s_or_b64 exec, exec, s[16:17]
	v_cmp_lt_i32_e32 vcc, -2, v24
	v_add_u32_e32 v24, 4, v61
	s_and_saveexec_b64 s[16:17], vcc
	s_cbranch_execz .LBB0_140
	v_lshl_add_u64 v[4:5], v[8:9], 0, v[24:25]
	v_lshlrev_b64 v[4:5], 12, v[4:5]
	v_lshl_add_u64 v[4:5], v[30:31], 0, v[4:5]
	v_mov_b32_e32 v4, v116
	v_mov_b32_e32 v5, v117
	v_mov_b32_e32 v6, v118
	v_mov_b32_e32 v7, v119
	ds_read_b32 v48, v23 offset:16
	v_pk_mul_f32 v[6:7], v[2:3], v[6:7]
	v_pk_mul_f32 v[4:5], v[0:1], v[4:5]
	s_waitcnt lgkmcnt(0)
	v_pk_fma_f32 v[44:45], v[6:7], v[48:49], v[44:45] op_sel_hi:[1,0,1] neg_lo:[1,0,0] neg_hi:[1,0,0]
	v_pk_fma_f32 v[46:47], v[4:5], v[48:49], v[46:47] op_sel_hi:[1,0,1] neg_lo:[1,0,0] neg_hi:[1,0,0]
.LBB0_140:
	s_or_b64 exec, exec, s[16:17]
	v_add_co_u32_e32 v4, vcc, 0xabc4000, v18
	ds_read_b32 v48, v59 offset:16
	s_nop 0
	v_addc_co_u32_e32 v5, vcc, 0, v19, vcc
	v_mov_b32_e32 v4, v88
	v_mov_b32_e32 v5, v89
	v_mov_b32_e32 v6, v90
	v_mov_b32_e32 v7, v91
	v_pk_mul_f32 v[62:63], v[2:3], v[6:7]
	v_pk_mul_f32 v[64:65], v[0:1], v[4:5]
	s_waitcnt lgkmcnt(0)
	v_pk_mul_f32 v[6:7], v[62:63], v[48:49] op_sel_hi:[1,0]
	v_pk_mul_f32 v[4:5], v[64:65], v[48:49] op_sel_hi:[1,0]
	v_pk_fma_f32 v[44:45], v[62:63], v[48:49], v[44:45] op_sel_hi:[1,0,1]
	v_pk_fma_f32 v[46:47], v[64:65], v[48:49], v[46:47] op_sel_hi:[1,0,1]
	v_add_u32_e32 v48, 5, v60
	v_min_u32_e32 v49, v48, v39
	v_cvt_f32_ubyte0_e32 v49, v49
	v_rcp_iflag_f32_e32 v62, v49
	s_nop 0
	v_pk_fma_f32 v[64:65], v[44:45], v[62:63], v[6:7] op_sel_hi:[1,0,1] neg_lo:[0,0,1] neg_hi:[0,0,1]
	v_pk_fma_f32 v[62:63], v[46:47], v[62:63], v[4:5] op_sel_hi:[1,0,1] neg_lo:[0,0,1] neg_hi:[0,0,1]
	s_nop 0
	v_cvt_pk_bf16_f32 v62, v62, v63
	v_cvt_pk_bf16_f32 v63, v64, v65
	v_add_co_u32_e32 v64, vcc, 0x16562000, v42
	s_nop 1
	v_addc_co_u32_e32 v65, vcc, 0, v43, vcc
	global_store_dwordx2 v[64:65], v[62:63], off
	s_and_saveexec_b64 s[16:17], s[38:39]
	s_cbranch_execz .LBB0_142
	s_load_dwordx2 s[18:19], s[0:1], 0x150
	s_waitcnt lgkmcnt(0)
	v_lshl_add_u64 v[62:63], s[18:19], 0, v[16:17]
	v_add_co_u32_e32 v62, vcc, 0xffffd000, v62
	s_nop 1
	v_addc_co_u32_e32 v63, vcc, -1, v63, vcc
	global_store_dwordx4 v[62:63], v[4:7], off
.LBB0_142:
	s_or_b64 exec, exec, s[16:17]
	v_cmp_lt_i32_e32 vcc, -2, v24
	v_add_u32_e32 v24, 5, v61
	s_and_saveexec_b64 s[16:17], vcc
	s_cbranch_execz .LBB0_144
	v_lshl_add_u64 v[4:5], v[8:9], 0, v[24:25]
	v_lshlrev_b64 v[4:5], 12, v[4:5]
	v_lshl_add_u64 v[4:5], v[30:31], 0, v[4:5]
	v_mov_b32_e32 v4, v120
	v_mov_b32_e32 v5, v121
	v_mov_b32_e32 v6, v122
	v_mov_b32_e32 v7, v123
	ds_read_b32 v62, v23 offset:20
	v_pk_mul_f32 v[6:7], v[2:3], v[6:7]
	v_pk_mul_f32 v[4:5], v[0:1], v[4:5]
	s_waitcnt lgkmcnt(0)
	v_pk_fma_f32 v[44:45], v[6:7], v[62:63], v[44:45] op_sel_hi:[1,0,1] neg_lo:[1,0,0] neg_hi:[1,0,0]
	v_pk_fma_f32 v[46:47], v[4:5], v[62:63], v[46:47] op_sel_hi:[1,0,1] neg_lo:[1,0,0] neg_hi:[1,0,0]
.LBB0_144:
	s_or_b64 exec, exec, s[16:17]
	v_add_co_u32_e32 v4, vcc, 0xabc5000, v18
	ds_read_b32 v62, v59 offset:20
	s_nop 0
	v_addc_co_u32_e32 v5, vcc, 0, v19, vcc
	v_mov_b32_e32 v4, v92
	v_mov_b32_e32 v5, v93
	v_mov_b32_e32 v6, v94
	v_mov_b32_e32 v7, v95
	v_pk_mul_f32 v[64:65], v[2:3], v[6:7]
	v_pk_mul_f32 v[66:67], v[0:1], v[4:5]
	s_waitcnt lgkmcnt(0)
	v_pk_mul_f32 v[6:7], v[64:65], v[62:63] op_sel_hi:[1,0]
	v_pk_mul_f32 v[4:5], v[66:67], v[62:63] op_sel_hi:[1,0]
	v_pk_fma_f32 v[44:45], v[64:65], v[62:63], v[44:45] op_sel_hi:[1,0,1]
	v_pk_fma_f32 v[46:47], v[66:67], v[62:63], v[46:47] op_sel_hi:[1,0,1]
	v_add_u32_e32 v62, 6, v60
	v_min_u32_e32 v49, v62, v39
	v_cvt_f32_ubyte0_e32 v49, v49
	v_rcp_iflag_f32_e32 v64, v49
	s_nop 0
	v_pk_fma_f32 v[66:67], v[44:45], v[64:65], v[6:7] op_sel_hi:[1,0,1] neg_lo:[0,0,1] neg_hi:[0,0,1]
	v_pk_fma_f32 v[64:65], v[46:47], v[64:65], v[4:5] op_sel_hi:[1,0,1] neg_lo:[0,0,1] neg_hi:[0,0,1]
	s_nop 0
	v_cvt_pk_bf16_f32 v64, v64, v65
	v_cvt_pk_bf16_f32 v65, v66, v67
	v_add_co_u32_e32 v66, vcc, 0x16562000, v42
	s_nop 1
	v_addc_co_u32_e32 v67, vcc, 0, v43, vcc
	v_cmp_lt_u32_e32 vcc, s93, v48
	global_store_dwordx2 v[66:67], v[64:65], off offset:2048
	s_and_saveexec_b64 s[16:17], vcc
	s_cbranch_execz .LBB0_146
	s_load_dwordx2 s[18:19], s[0:1], 0x150
	s_waitcnt lgkmcnt(0)
	v_lshl_add_u64 v[48:49], s[18:19], 0, v[16:17]
	v_add_co_u32_e32 v48, vcc, 0xffffe000, v48
	s_nop 1
	v_addc_co_u32_e32 v49, vcc, -1, v49, vcc
	global_store_dwordx4 v[48:49], v[4:7], off
; DI unsigned pk2(float lo, float hi) { const f32x2v v = {lo, hi}; const bf16x2v b = __builtin_convertvector(v, bf16x2v); return __builtin_bit_cast(unsigned, b); }
; DI void pool_prep(const Params& P, LAS unsigned char* lds) {
;     ...
;         if (it < 1024) { const int b = it >> 7, t0 = (it & 127) * 16; const size_t rb = (size_t)b * 2048;
;             f32x4 sum = {0.f, 0.f, 0.f, 0.f};
;             for (int j = 1; j < w; ++j) { const int tt = t0 - j; if (tt >= 0) { const float rs = rsl[15 - j]; sum += *(const f32x4*)(X + (rb + tt) * DM + c4) * g4 * rs; } }
; #pragma unroll 8
;             for (int t = t0; t < t0 + 16; ++t) { const float rs = rsl[t - t0 + 15]; const f32x4 cur = *(const f32x4*)(X + (rb + t) * DM + c4) * g4 * rs;
;                 sum += cur; const float ic = __builtin_amdgcn_rcpf((float)(t + 1 < w ? t + 1 : w)); const f32x4 d = sum * ic - cur;
;                 u32x2 o; o.x = pk2(d[0], d[1]); o.y = pk2(d[2], d[3]); *(u32x2*)(DF + (rb + t) * DM + c4) = o;
;                 if (t >= 2033) *(f32x4*)(P.out + OUT_POOLP + ((size_t)b * 15 + (t - 2033)) * DM + c4) = cur;
;                 const int tt = t - w + 1; if (tt >= 0) { const float r2 = rsl[tt - t0 + 15]; sum -= *(const f32x4*)(X + (rb + tt) * DM + c4) * g4 * r2; } }
.LBB0_146:
	s_or_b64 exec, exec, s[16:17]
	v_cmp_lt_i32_e32 vcc, -2, v24
	v_add_u32_e32 v24, 6, v61
	s_and_saveexec_b64 s[16:17], vcc
	s_cbranch_execz .LBB0_148
	v_lshl_add_u64 v[4:5], v[8:9], 0, v[24:25]
	v_lshlrev_b64 v[4:5], 12, v[4:5]
	v_lshl_add_u64 v[4:5], v[30:31], 0, v[4:5]
	v_mov_b32_e32 v4, v124
	v_mov_b32_e32 v5, v125
	v_mov_b32_e32 v6, v126
	v_mov_b32_e32 v7, v127
	ds_read_b32 v48, v23 offset:24
	v_pk_mul_f32 v[6:7], v[2:3], v[6:7]
	v_pk_mul_f32 v[4:5], v[0:1], v[4:5]
	s_waitcnt lgkmcnt(0)
	v_pk_fma_f32 v[44:45], v[6:7], v[48:49], v[44:45] op_sel_hi:[1,0,1] neg_lo:[1,0,0] neg_hi:[1,0,0]
	v_pk_fma_f32 v[46:47], v[4:5], v[48:49], v[46:47] op_sel_hi:[1,0,1] neg_lo:[1,0,0] neg_hi:[1,0,0]
.LBB0_148:
	s_or_b64 exec, exec, s[16:17]
	v_add_co_u32_e32 v4, vcc, 0xabc6000, v18
	ds_read_b32 v48, v59 offset:24
	s_nop 0
	v_addc_co_u32_e32 v5, vcc, 0, v19, vcc
	v_mov_b32_e32 v4, v96
	v_mov_b32_e32 v5, v97
	v_mov_b32_e32 v6, v98
	v_mov_b32_e32 v7, v99
	v_add_u32_e32 v63, 7, v60
	v_pk_mul_f32 v[64:65], v[2:3], v[6:7]
	v_pk_mul_f32 v[66:67], v[0:1], v[4:5]
	s_waitcnt lgkmcnt(0)
	v_pk_mul_f32 v[6:7], v[64:65], v[48:49] op_sel_hi:[1,0]
	v_pk_mul_f32 v[4:5], v[66:67], v[48:49] op_sel_hi:[1,0]
	v_pk_fma_f32 v[44:45], v[64:65], v[48:49], v[44:45] op_sel_hi:[1,0,1]
	v_pk_fma_f32 v[48:49], v[66:67], v[48:49], v[46:47] op_sel_hi:[1,0,1]
	v_min_u32_e32 v46, v63, v39
	v_cvt_f32_ubyte0_e32 v46, v46
	v_rcp_iflag_f32_e32 v46, v46
	s_nop 0
	v_pk_fma_f32 v[64:65], v[44:45], v[46:47], v[6:7] op_sel_hi:[1,0,1] neg_lo:[0,0,1] neg_hi:[0,0,1]
	v_pk_fma_f32 v[46:47], v[48:49], v[46:47], v[4:5] op_sel_hi:[1,0,1] neg_lo:[0,0,1] neg_hi:[0,0,1]
	s_nop 0
	v_cvt_pk_bf16_f32 v46, v46, v47
	v_cvt_pk_bf16_f32 v47, v64, v65
	v_add_co_u32_e32 v64, vcc, 0x16563000, v42
	s_nop 1
	v_addc_co_u32_e32 v65, vcc, 0, v43, vcc
	v_cmp_lt_u32_e32 vcc, s93, v62
	global_store_dwordx2 v[64:65], v[46:47], off
	s_and_saveexec_b64 s[16:17], vcc
	s_cbranch_execz .LBB0_150
	s_load_dwordx2 s[18:19], s[0:1], 0x150
	s_waitcnt lgkmcnt(0)
	v_lshl_add_u64 v[46:47], s[18:19], 0, v[16:17]
	global_store_dwordx4 v[46:47], v[4:7], off offset:-4096
.LBB0_150:
	s_or_b64 exec, exec, s[16:17]
	v_cmp_lt_i32_e32 vcc, -2, v24
	v_add_u32_e32 v24, 7, v61
	s_and_saveexec_b64 s[16:17], vcc
	s_cbranch_execz .LBB0_152
	v_lshl_add_u64 v[4:5], v[8:9], 0, v[24:25]
	v_lshlrev_b64 v[4:5], 12, v[4:5]
	v_lshl_add_u64 v[4:5], v[30:31], 0, v[4:5]
	v_mov_b32_e32 v4, v128
	v_mov_b32_e32 v5, v129
	v_mov_b32_e32 v6, v130
	v_mov_b32_e32 v7, v131
	ds_read_b32 v46, v23 offset:28
	v_pk_mul_f32 v[6:7], v[2:3], v[6:7]
	v_pk_mul_f32 v[4:5], v[0:1], v[4:5]
	s_waitcnt lgkmcnt(0)
	v_pk_fma_f32 v[44:45], v[6:7], v[46:47], v[44:45] op_sel_hi:[1,0,1] neg_lo:[1,0,0] neg_hi:[1,0,0]
	v_pk_fma_f32 v[48:49], v[4:5], v[46:47], v[48:49] op_sel_hi:[1,0,1] neg_lo:[1,0,0] neg_hi:[1,0,0]
.LBB0_152:
	s_or_b64 exec, exec, s[16:17]
	v_add_co_u32_e32 v4, vcc, 0xabc7000, v18
	ds_read_b32 v62, v59 offset:28
	s_nop 0
	v_addc_co_u32_e32 v5, vcc, 0, v19, vcc
	v_mov_b32_e32 v4, v100
	v_mov_b32_e32 v5, v101
	v_mov_b32_e32 v6, v102
	v_mov_b32_e32 v7, v103
	v_add_co_u32_e32 v42, vcc, 0x16563000, v42
	v_pk_mul_f32 v[18:19], v[2:3], v[6:7]
	s_waitcnt lgkmcnt(0)
	v_pk_mul_f32 v[6:7], v[18:19], v[62:63] op_sel_hi:[1,0]
	v_pk_fma_f32 v[46:47], v[18:19], v[62:63], v[44:45] op_sel_hi:[1,0,1]
	v_add_u32_e32 v18, 8, v60
	v_min_u32_e32 v18, v18, v39
	v_cvt_f32_ubyte0_e32 v18, v18
	v_rcp_iflag_f32_e32 v18, v18
	v_pk_mul_f32 v[64:65], v[0:1], v[4:5]
	v_addc_co_u32_e32 v43, vcc, 0, v43, vcc
	v_pk_mul_f32 v[4:5], v[64:65], v[62:63] op_sel_hi:[1,0]
	v_pk_fma_f32 v[44:45], v[64:65], v[62:63], v[48:49] op_sel_hi:[1,0,1]
	v_pk_fma_f32 v[48:49], v[46:47], v[18:19], v[6:7] op_sel_hi:[1,0,1] neg_lo:[0,0,1] neg_hi:[0,0,1]
	v_pk_fma_f32 v[18:19], v[44:45], v[18:19], v[4:5] op_sel_hi:[1,0,1] neg_lo:[0,0,1] neg_hi:[0,0,1]
	v_cmp_lt_u32_e32 vcc, s93, v63
	v_cvt_pk_bf16_f32 v18, v18, v19
	v_cvt_pk_bf16_f32 v19, v48, v49
	global_store_dwordx2 v[42:43], v[18:19], off offset:2048
	s_and_saveexec_b64 s[16:17], vcc
	s_cbranch_execz .LBB0_154
	s_load_dwordx2 s[18:19], s[0:1], 0x150
	s_waitcnt lgkmcnt(0)
	v_lshl_add_u64 v[18:19], s[18:19], 0, v[16:17]
	global_store_dwordx4 v[18:19], v[4:7], off
.LBB0_154:
	s_or_b64 exec, exec, s[16:17]
	v_cmp_lt_i32_e32 vcc, -2, v24
	s_and_saveexec_b64 s[16:17], vcc
	s_cbranch_execz .LBB0_123
	v_add_u32_e32 v24, 8, v61
	v_lshl_add_u64 v[4:5], v[8:9], 0, v[24:25]
	v_lshlrev_b64 v[4:5], 12, v[4:5]
	v_lshl_add_u64 v[4:5], v[30:31], 0, v[4:5]
	v_mov_b32_e32 v4, v132
	v_mov_b32_e32 v5, v133
	v_mov_b32_e32 v6, v134
	v_mov_b32_e32 v7, v135
	ds_read_b32 v18, v23 offset:32
	v_pk_mul_f32 v[6:7], v[2:3], v[6:7]
	v_pk_mul_f32 v[4:5], v[0:1], v[4:5]
	s_waitcnt lgkmcnt(0)
	v_pk_fma_f32 v[46:47], v[6:7], v[18:19], v[46:47] op_sel_hi:[1,0,1] neg_lo:[1,0,0] neg_hi:[1,0,0]
	v_pk_fma_f32 v[44:45], v[4:5], v[18:19], v[44:45] op_sel_hi:[1,0,1] neg_lo:[1,0,0] neg_hi:[1,0,0]
	s_branch .LBB0_123
